# adds: next-tile LDS address adds moved from the PV2a gap into the last two QK MFMA shadows (still the 12-state hazard filler), SALU spread evenly over QK gaps
# baseline (speedup 1.0000x reference)
; #define MFMA32(a, b, c) __builtin_amdgcn_mfma_f32_32x32x16_bf16((a), (b), (c), 0, 0, 0)
; #define VLOAD(dst, sbv, q) do { _Pragma("unroll") for (int d_ = 0; d_ < 4; ++d_) dst[d_] = *(const lds_bf16x8*)((sbv) + vo[q] + d_ * 4096); } while (0)
; #define FENCE __builtin_amdgcn_sched_barrier(0)
; DI void diff_unit(KP p, int l, int b, int h, int qb, int isctx, float lamv, float lam_init, char* ldsc) {
;     ...
;   for (int kt = 0; kt < nt - 1; ++kt) {
;     asm volatile("s_waitcnt vmcnt(0)" ::: "memory");
;     __builtin_amdgcn_s_barrier();
;     const int stg1 = stg == 2 ? 0 : stg + 1;
;     if (kt + 2 < nt) { const int s2_ = stg >= 1 ? stg - 1 : 2; DISSUE(kt + 2, s2_); }
;     if (need) {
; #pragma unroll
;       for (int d = 0; d < 4; ++d) o[d] *= alpha;
;     }
;     const lds_u8* sbv = L + stg * STG + 16384;
;     const lds_u8* sbk = L + stg1 * STG + comp * 8192;
;     bf16x8 kf[2][4];
;     f32x16 st[2];
; #pragma unroll
;     for (int t = 0; t < 2; ++t)
; #pragma unroll
;       for (int ks = 0; ks < 4; ++ks) kf[t][ks] = *(const lds_bf16x8*)(sbk + ko[ks] + t * 4096);
;     FENCE;
;     pv_grp(o, vA, P[0]); pv_grp(o, vB, P[1]);
;     VLOAD(vA, sbv, 2); VLOAD(vB, sbv, 3);
;     FENCE;
; #pragma unroll
;     for (int i = 0; i < 16; ++i) { st[0][i] = 0.f; st[1][i] = 0.f; }
; #pragma unroll
;     for (int ks = 0; ks < 4; ++ks) st[0] = MFMA32(kf[0][ks], qf[ks], st[0]);
; #pragma unroll
;     for (int ks = 0; ks < 4; ++ks) st[1] = MFMA32(kf[1][ks], qf[ks], st[1]);
;     FENCE;
;     pv_grp(o, vA, P[2]);
;     const float mx = tile_max(st);
;     need = !__all(mx <= m + 8.0f);
;     const float mn = need ? fmaxf(m, mx) : m;
;     alpha = __builtin_amdgcn_exp2f(m - mn);
;     FENCE;
;     float ps = exp_pack1<0>(st, mn, P[0]);
;     ps += exp_pack1<1>(st, mn, P[1]);
;     ps += exp_pack1<2>(st, mn, P[2]);
;     pv_grp(o, vB, P[3]);
;     ps += exp_pack1<3>(st, mn, P[3]);
; #pragma unroll
;     for (int q = 0; q < 4; ++q) { __builtin_amdgcn_sched_group_barrier(0x402, 18, 0); __builtin_amdgcn_sched_group_barrier(0x008, 1, 0); }
.LBB0_475:
.LBB0_477:
	ds_read_b128 v[154:157], v136
	ds_read_b128 v[192:195], v136 offset:4096
	ds_read_b128 v[196:199], v137
	ds_read_b128 v[200:203], v137 offset:4096
	ds_read_b128 v[204:207], v138
	ds_read_b128 v[208:211], v138 offset:4096
	ds_read_b128 v[212:215], v139
	ds_read_b128 v[216:219], v139 offset:4096
	s_waitcnt lgkmcnt(8)
	v_mfma_f32_32x32x16_bf16 v[50:65], v[86:89], v[66:69], v[50:65]
	s_add_i32 s2, s17, 1
	s_and_b32 s16, s2, 3
	s_lshl_b32 s15, s16, 15
	ds_read_b128 v[220:223], v248 offset:24576
	ds_read_b128 v[224:227], v248 offset:28672
	v_mfma_f32_32x32x16_bf16 v[34:49], v[82:85], v[66:69], v[34:49]
	v_cvt_pk_bf16_f32 v118, v228, v229
	v_cvt_pk_bf16_f32 v119, v230, v231
	v_cvt_pk_bf16_f32 v120, v232, v233
	v_cvt_pk_bf16_f32 v121, v234, v235
	v_mfma_f32_32x32x16_bf16 v[18:33], v[78:81], v[66:69], v[18:33]
	v_cvt_pk_bf16_f32 v114, v236, v237
	v_cvt_pk_bf16_f32 v115, v238, v239
	v_cvt_pk_bf16_f32 v116, v240, v241
	v_cvt_pk_bf16_f32 v117, v242, v243
	v_mfma_f32_32x32x16_bf16 v[2:17], v[74:77], v[66:69], v[2:17]
	v_mov_b64_e32 v[66:67], v[252:253]
	v_mov_b64_e32 v[68:69], v[252:253]
	v_mov_b64_e32 v[74:75], v[252:253]
	v_mfma_f32_32x32x16_bf16 v[50:65], v[126:129], v[70:73], v[50:65]
	v_mov_b64_e32 v[76:77], v[252:253]
	v_mov_b64_e32 v[78:79], v[252:253]
	v_mov_b64_e32 v[80:81], v[252:253]
	ds_read_b128 v[126:129], v248 offset:20480
	v_mfma_f32_32x32x16_bf16 v[34:49], v[122:125], v[70:73], v[34:49]
	ds_read_b128 v[122:125], v248 offset:16384
	ds_read_b128 v[228:231], v255 offset:16384
	ds_read_b128 v[232:235], v255 offset:20480
	v_mfma_f32_32x32x16_bf16 v[18:33], v[94:97], v[70:73], v[18:33]
	ds_read_b128 v[236:239], v255 offset:24576
	ds_read_b128 v[240:243], v255 offset:28672
	v_mfma_f32_32x32x16_bf16 v[2:17], v[90:93], v[70:73], v[2:17]
	v_mov_b64_e32 v[70:71], v[252:253]
	v_mov_b64_e32 v[72:73], v[252:253]
	s_add_i32 s18, s3, 0xc0
	s_add_i32 s19, s10, 64
	s_cmp_eq_u32 s11, 0
	s_cselect_b32 s19, s18, s19
	s_waitcnt lgkmcnt(8)
	v_mfma_f32_32x32x16_bf16 v[82:97], v[154:157], v[98:101], v[66:81]
	s_add_i32 s11, s11, 1
	s_add_i32 s10, s10, 64
	s_mul_i32 s19, s19, 0x1600
	s_add_u32 s18, s22, s19
	s_addc_u32 s19, s23, 0
	v_mfma_f32_32x32x16_bf16 v[66:81], v[192:195], v[98:101], v[66:81]
	s_add_i32 s24, s17, 3
	s_and_b32 s24, s24, 3
	s_lshl_b32 s24, s24, 15
	s_add_i32 s24, s13, s24
	s_mov_b32 m0, s24
	v_mfma_f32_32x32x16_bf16 v[66:81], v[200:203], v[102:105], v[66:81]
	global_load_lds_dwordx4 v244, s[18:19]
	s_add_i32 m0, s24, 0x2000
	v_mfma_f32_32x32x16_bf16 v[82:97], v[196:199], v[102:105], v[82:97]
	global_load_lds_dwordx4 v245, s[18:19]
	s_add_i32 m0, s24, 0x4000
	v_mfma_f32_32x32x16_bf16 v[66:81], v[208:211], v[106:109], v[66:81]
	global_load_lds_dwordx4 v246, s[20:21]
	s_add_i32 m0, s24, 0x6000
	v_mfma_f32_32x32x16_bf16 v[82:97], v[204:207], v[106:109], v[82:97]
	global_load_lds_dwordx4 v247, s[20:21]
	s_add_u32 s20, s20, 0x80
	s_addc_u32 s21, s21, 0
	v_mfma_f32_32x32x16_bf16 v[66:81], v[216:219], v[110:113], v[66:81]
	s_add_i32 s18, s16, 1
	s_and_b32 s18, s18, 3
	s_lshl_b32 s18, s18, 15
	s_add_i32 s18, s18, s14
	v_add_u32_e32 v251, s15, v150
	v_add_u32_e32 v249, s15, v151
	v_mfma_f32_32x32x16_bf16 v[82:97], v[212:215], v[110:113], v[82:97]
	v_add_u32_e32 v136, s18, v141
	v_add_u32_e32 v137, s18, v145
	v_add_u32_e32 v138, s18, v147
	v_add_u32_e32 v139, s18, v148
	v_add_u32_e32 v248, s15, v149
	v_add_u32_e32 v255, s15, v146
	s_waitcnt lgkmcnt(0)
	v_mfma_f32_32x32x16_bf16 v[50:65], v[122:125], v[118:121], v[50:65]
	s_mov_b32 s17, s16
	s_cmpk_lg_i32 s11, 0x83
	v_mfma_f32_32x32x16_bf16 v[34:49], v[126:129], v[118:121], v[34:49]
	s_nop 0
	v_exp_f32_e32 v122, v82
	v_exp_f32_e32 v124, v83
	v_exp_f32_e32 v126, v84
	v_exp_f32_e32 v128, v85
	v_exp_f32_e32 v156, v86
	v_mfma_f32_32x32x16_bf16 v[18:33], v[220:223], v[118:121], v[18:33]
	v_exp_f32_e32 v192, v87
	v_exp_f32_e32 v194, v88
	v_exp_f32_e32 v196, v89
	v_exp_f32_e32 v123, v90
	v_exp_f32_e32 v125, v91
	v_mfma_f32_32x32x16_bf16 v[2:17], v[224:227], v[118:121], v[2:17]
	v_exp_f32_e32 v127, v92
	v_exp_f32_e32 v129, v93
	v_exp_f32_e32 v157, v94
	v_exp_f32_e32 v193, v95
	v_exp_f32_e32 v195, v96
	v_mfma_f32_32x32x16_bf16 v[50:65], v[228:231], v[114:117], v[50:65]
	v_exp_f32_e32 v197, v97
	v_exp_f32_e32 v228, v66
	v_exp_f32_e32 v229, v67
	v_exp_f32_e32 v230, v68
	v_exp_f32_e32 v231, v69
	v_mfma_f32_32x32x16_bf16 v[34:49], v[232:235], v[114:117], v[34:49]
	v_exp_f32_e32 v232, v70
	v_exp_f32_e32 v233, v71
	v_exp_f32_e32 v234, v72
	v_exp_f32_e32 v235, v73
	v_pk_add_f32 v[92:93], v[124:125], v[122:123]
	v_pk_add_f32 v[92:93], v[126:127], v[92:93]
	v_mfma_f32_32x32x16_bf16 v[18:33], v[236:239], v[114:117], v[18:33]
	v_exp_f32_e32 v236, v74
	v_exp_f32_e32 v237, v75
	v_exp_f32_e32 v238, v76
	v_exp_f32_e32 v239, v77
	v_pk_add_f32 v[92:93], v[128:129], v[92:93]
	v_pk_add_f32 v[92:93], v[156:157], v[92:93]
	v_mfma_f32_32x32x16_bf16 v[2:17], v[240:243], v[114:117], v[2:17]
	v_exp_f32_e32 v240, v78
	v_exp_f32_e32 v241, v79
	v_exp_f32_e32 v242, v80
	v_exp_f32_e32 v243, v81
	v_pk_add_f32 v[92:93], v[192:193], v[92:93]
	v_pk_add_f32 v[92:93], v[194:195], v[92:93]
	v_pk_add_f32 v[92:93], v[196:197], v[92:93]
	ds_read_b128 v[78:81], v251 offset:24576
	ds_read_b128 v[74:77], v251 offset:28672
	v_pk_add_f32 v[198:199], v[228:229], v[230:231]
	v_pk_add_f32 v[198:199], v[232:233], v[198:199]
	v_pk_add_f32 v[198:199], v[234:235], v[198:199]
	v_pk_add_f32 v[198:199], v[236:237], v[198:199]
	v_pk_add_f32 v[198:199], v[238:239], v[198:199]
	v_pk_add_f32 v[198:199], v[240:241], v[198:199]
	v_pk_add_f32 v[198:199], v[242:243], v[198:199]
	v_pk_add_f32 v[198:199], v[198:199], v[92:93]
	v_max_f32_e32 v200, v198, v199
	v_cmp_lt_f32_e32 vcc, 0x43000000, v200
	s_cbranch_vccnz .Ldiff_rare
